# fp8 down GEMM: unscaled v_mfma_f32_16x16x128_f8f6f4 (same fp8 e4m3 operands, unit scales were 2^0) instead of the scaled form with its ld_scale prefix
# speedup vs baseline: 1.0086x; 1.0055x over previous
.LPF_462:
	s_add_u32 s24, s26, 0x100
	s_addc_u32 s25, s27, 0
	s_add_i32 s43, 0, 0x10000
	s_cmp_eq_u32 s42, 40
	s_cselect_b32 s31, s21, s25
	s_cselect_b32 s30, s20, s24
	s_cselect_b32 s29, s23, s13
	s_cselect_b32 s28, s22, s11
	s_add_i32 s60, 0, 0x14000
	v_add_u32_e32 v2, s43, v187
	v_add_u32_e32 v14, s60, v187
	ds_read_b128 v[18:21], v2
	ds_read_b128 v[22:25], v2 offset:1024
	ds_read_b128 v[26:29], v2 offset:2048
	ds_read_b128 v[30:33], v2 offset:3072
	ds_read_b128 v[2:5], v14
	ds_read_b128 v[6:9], v14 offset:1024
	ds_read_b128 v[10:13], v14 offset:2048
	ds_read_b128 v[14:17], v14 offset:3072
	v_lshl_add_u64 v[182:183], s[26:27], 0, v[170:171]
	s_add_i32 m0, s39, 0xc000
	ds_read_b128 v[174:177], v188
	ds_read_b128 v[178:181], v188 offset:1024
	ds_read_b128 v[190:193], v188 offset:2048
	ds_read_b128 v[194:197], v188 offset:3072
	ds_read_b128 v[206:209], v188 offset:4096
	ds_read_b128 v[210:213], v188 offset:5120
	ds_read_b128 v[214:217], v188 offset:6144
	ds_read_b128 v[218:221], v188 offset:7168
	global_load_lds_dwordx4 v[182:183], off
	v_lshl_add_u64 v[182:183], s[26:27], 0, v[172:173]
	s_add_i32 m0, s39, 0xe000
	s_nop 0
	global_load_lds_dwordx4 v[182:183], off
	s_waitcnt vmcnt(8)
	s_waitcnt lgkmcnt(0)
	s_setprio 1
	s_barrier
	v_mfma_f32_16x16x128_f8f6f4 v[160:163], v[18:25], v[174:181], 0
	v_mfma_f32_16x16x128_f8f6f4 v[156:159], v[26:33], v[174:181], 0
	v_mfma_f32_16x16x128_f8f6f4 v[144:147], v[18:25], v[190:197], 0
	v_mfma_f32_16x16x128_f8f6f4 v[140:143], v[26:33], v[190:197], 0
	v_mfma_f32_16x16x128_f8f6f4 v[128:131], v[18:25], v[206:213], 0
	v_mfma_f32_16x16x128_f8f6f4 v[124:127], v[26:33], v[206:213], 0
	v_mfma_f32_16x16x128_f8f6f4 v[112:115], v[18:25], v[214:221], 0
	v_mfma_f32_16x16x128_f8f6f4 v[108:111], v[26:33], v[214:221], 0
	v_mfma_f32_16x16x128_f8f6f4 v[152:155], v[2:9], v[174:181], 0
	v_mfma_f32_16x16x128_f8f6f4 v[148:151], v[10:17], v[174:181], 0
	v_mfma_f32_16x16x128_f8f6f4 v[136:139], v[2:9], v[190:197], 0
	v_mfma_f32_16x16x128_f8f6f4 v[132:135], v[10:17], v[190:197], 0
	v_mfma_f32_16x16x128_f8f6f4 v[120:123], v[2:9], v[206:213], 0
	v_mfma_f32_16x16x128_f8f6f4 v[116:119], v[10:17], v[206:213], 0
	v_mfma_f32_16x16x128_f8f6f4 v[104:107], v[2:9], v[214:221], 0
	v_mfma_f32_16x16x128_f8f6f4 v[100:103], v[10:17], v[214:221], 0
	s_barrier
	s_setprio 0
	s_add_i32 s26, s43, s38
	v_lshl_add_u64 v[174:175], s[28:29], 0, v[34:35]
	s_mov_b32 m0, s26
	ds_read_b128 v[190:193], v188 offset:16384
	ds_read_b128 v[194:197], v188 offset:17408
	ds_read_b128 v[206:209], v188 offset:18432
	ds_read_b128 v[210:213], v188 offset:19456
	ds_read_b128 v[214:217], v188 offset:20480
	ds_read_b128 v[218:221], v188 offset:21504
	ds_read_b128 v[240:243], v188 offset:22528
	ds_read_b128 v[244:247], v188 offset:23552
	global_load_lds_dwordx4 v[174:175], off
	s_add_i32 m0, s26, 0x2000
	s_add_u32 s26, s28, 0xb0000
	v_lshl_add_u64 v[176:177], s[28:29], 0, v[168:169]
	s_addc_u32 s27, s29, 0
	s_add_i32 s43, s60, s38
	global_load_lds_dwordx4 v[176:177], off
	v_lshl_add_u64 v[178:179], s[26:27], 0, v[34:35]
	s_mov_b32 m0, s43
	v_lshl_add_u64 v[180:181], s[30:31], 0, v[166:167]
	global_load_lds_dwordx4 v[178:179], off
	v_lshl_add_u64 v[178:179], s[26:27], 0, v[168:169]
	s_add_i32 m0, s43, 0x2000
	s_nop 0
	global_load_lds_dwordx4 v[178:179], off
	v_lshl_add_u64 v[178:179], s[30:31], 0, v[164:165]
	s_mov_b32 m0, s39
	s_nop 0
	global_load_lds_dwordx4 v[178:179], off
	s_mov_b32 m0, s44
	s_nop 0
	global_load_lds_dwordx4 v[180:181], off
	s_waitcnt vmcnt(8)
	s_waitcnt lgkmcnt(0)
	s_setprio 1
	s_barrier
	v_mfma_f32_16x16x128_f8f6f4 v[96:99], v[18:25], v[190:197], 0
	v_mfma_f32_16x16x128_f8f6f4 v[92:95], v[26:33], v[190:197], 0
	v_mfma_f32_16x16x128_f8f6f4 v[80:83], v[18:25], v[206:213], 0
	v_mfma_f32_16x16x128_f8f6f4 v[76:79], v[26:33], v[206:213], 0
	v_mfma_f32_16x16x128_f8f6f4 v[64:67], v[18:25], v[214:221], 0
	v_mfma_f32_16x16x128_f8f6f4 v[60:63], v[26:33], v[214:221], 0
	v_mfma_f32_16x16x128_f8f6f4 v[48:51], v[18:25], v[240:247], 0
	v_mfma_f32_16x16x128_f8f6f4 v[44:47], v[26:33], v[240:247], 0
	v_mfma_f32_16x16x128_f8f6f4 v[88:91], v[2:9], v[190:197], 0
	v_mfma_f32_16x16x128_f8f6f4 v[84:87], v[10:17], v[190:197], 0
	v_mfma_f32_16x16x128_f8f6f4 v[72:75], v[2:9], v[206:213], 0
	v_mfma_f32_16x16x128_f8f6f4 v[68:71], v[10:17], v[206:213], 0
	v_mfma_f32_16x16x128_f8f6f4 v[56:59], v[2:9], v[214:221], 0
	v_mfma_f32_16x16x128_f8f6f4 v[52:55], v[10:17], v[214:221], 0
	v_mfma_f32_16x16x128_f8f6f4 v[40:43], v[2:9], v[240:247], 0
	v_mfma_f32_16x16x128_f8f6f4 v[36:39], v[10:17], v[240:247], 0
	s_barrier
	s_setprio 0
	s_add_i32 s43, 0, 0x18000
	s_add_i32 s60, 0, 0x1c000
	v_add_u32_e32 v14, s43, v187
	v_add_u32_e32 v30, s60, v187
	ds_read_b128 v[2:5], v14
	ds_read_b128 v[6:9], v14 offset:1024
	ds_read_b128 v[10:13], v14 offset:2048
	ds_read_b128 v[14:17], v14 offset:3072
	ds_read_b128 v[18:21], v30
	ds_read_b128 v[22:25], v30 offset:1024
	ds_read_b128 v[26:29], v30 offset:2048
	ds_read_b128 v[30:33], v30 offset:3072
	s_add_u32 s26, s30, 0xb0000
	s_addc_u32 s27, s31, 0
	s_mov_b32 m0, s45
	v_lshl_add_u64 v[182:183], s[26:27], 0, v[164:165]
	ds_read_b128 v[190:193], v188 offset:32768
	ds_read_b128 v[194:197], v188 offset:33792
	ds_read_b128 v[206:209], v188 offset:34816
	ds_read_b128 v[210:213], v188 offset:35840
	ds_read_b128 v[214:217], v188 offset:36864
	ds_read_b128 v[218:221], v188 offset:37888
	ds_read_b128 v[240:243], v188 offset:38912
	ds_read_b128 v[244:247], v188 offset:39936
	global_load_lds_dwordx4 v[182:183], off
	v_lshl_add_u64 v[182:183], s[26:27], 0, v[166:167]
	s_mov_b32 m0, s46
	s_nop 0
	global_load_lds_dwordx4 v[182:183], off
	s_waitcnt vmcnt(8)
	s_waitcnt lgkmcnt(0)
	s_setprio 1
	s_barrier
	v_mfma_f32_16x16x128_f8f6f4 v[160:163], v[2:9], v[190:197], v[160:163]
	v_mfma_f32_16x16x128_f8f6f4 v[156:159], v[10:17], v[190:197], v[156:159]
	v_mfma_f32_16x16x128_f8f6f4 v[144:147], v[2:9], v[206:213], v[144:147]
	v_mfma_f32_16x16x128_f8f6f4 v[140:143], v[10:17], v[206:213], v[140:143]
	v_mfma_f32_16x16x128_f8f6f4 v[128:131], v[2:9], v[214:221], v[128:131]
	v_mfma_f32_16x16x128_f8f6f4 v[124:127], v[10:17], v[214:221], v[124:127]
	v_mfma_f32_16x16x128_f8f6f4 v[112:115], v[2:9], v[240:247], v[112:115]
	v_mfma_f32_16x16x128_f8f6f4 v[108:111], v[10:17], v[240:247], v[108:111]
	v_mfma_f32_16x16x128_f8f6f4 v[152:155], v[18:25], v[190:197], v[152:155]
	v_mfma_f32_16x16x128_f8f6f4 v[148:151], v[26:33], v[190:197], v[148:151]
	v_mfma_f32_16x16x128_f8f6f4 v[136:139], v[18:25], v[206:213], v[136:139]
	v_mfma_f32_16x16x128_f8f6f4 v[132:135], v[26:33], v[206:213], v[132:135]
	v_mfma_f32_16x16x128_f8f6f4 v[120:123], v[18:25], v[214:221], v[120:123]
	v_mfma_f32_16x16x128_f8f6f4 v[116:119], v[26:33], v[214:221], v[116:119]
	v_mfma_f32_16x16x128_f8f6f4 v[104:107], v[18:25], v[240:247], v[104:107]
	v_mfma_f32_16x16x128_f8f6f4 v[100:103], v[26:33], v[240:247], v[100:103]
	s_barrier
	s_setprio 0
	s_add_i32 s26, s43, s38
	v_lshl_add_u64 v[174:175], v[174:175], 0, s[18:19]
	s_mov_b32 m0, s26
	ds_read_b128 v[190:193], v188 offset:49152
	ds_read_b128 v[194:197], v188 offset:50176
	ds_read_b128 v[206:209], v188 offset:51200
	ds_read_b128 v[210:213], v188 offset:52224
	ds_read_b128 v[214:217], v188 offset:53248
	ds_read_b128 v[218:221], v188 offset:54272
	ds_read_b128 v[240:243], v188 offset:55296
	ds_read_b128 v[244:247], v188 offset:56320
	global_load_lds_dwordx4 v[174:175], off
	s_add_i32 m0, s26, 0x2000
	s_add_u32 s26, s28, 0xb0080
	v_lshl_add_u64 v[174:175], v[176:177], 0, s[18:19]
	s_addc_u32 s27, s29, 0
	s_add_i32 s28, s60, s38
	global_load_lds_dwordx4 v[174:175], off
	v_lshl_add_u64 v[174:175], s[26:27], 0, v[34:35]
	s_mov_b32 m0, s28
	s_nop 0
	global_load_lds_dwordx4 v[174:175], off
	v_lshl_add_u64 v[174:175], s[26:27], 0, v[168:169]
	s_add_i32 m0, s28, 0x2000
	s_nop 0
	global_load_lds_dwordx4 v[174:175], off
	v_lshl_add_u64 v[174:175], v[178:179], 0, s[18:19]
	s_mov_b32 m0, s47
	s_nop 0
	global_load_lds_dwordx4 v[174:175], off
	v_lshl_add_u64 v[174:175], v[180:181], 0, s[18:19]
	s_mov_b32 m0, s52
	s_nop 0
	global_load_lds_dwordx4 v[174:175], off
	s_waitcnt vmcnt(8)
	s_waitcnt lgkmcnt(0)
	s_setprio 1
	s_barrier
	v_mfma_f32_16x16x128_f8f6f4 v[96:99], v[2:9], v[190:197], v[96:99]
	v_mfma_f32_16x16x128_f8f6f4 v[92:95], v[10:17], v[190:197], v[92:95]
	v_mfma_f32_16x16x128_f8f6f4 v[80:83], v[2:9], v[206:213], v[80:83]
	v_mfma_f32_16x16x128_f8f6f4 v[76:79], v[10:17], v[206:213], v[76:79]
	v_mfma_f32_16x16x128_f8f6f4 v[64:67], v[2:9], v[214:221], v[64:67]
	v_mfma_f32_16x16x128_f8f6f4 v[60:63], v[10:17], v[214:221], v[60:63]
	v_mfma_f32_16x16x128_f8f6f4 v[48:51], v[2:9], v[240:247], v[48:51]
	v_mfma_f32_16x16x128_f8f6f4 v[44:47], v[10:17], v[240:247], v[44:47]
	v_mfma_f32_16x16x128_f8f6f4 v[88:91], v[18:25], v[190:197], v[88:91]
	v_mfma_f32_16x16x128_f8f6f4 v[84:87], v[26:33], v[190:197], v[84:87]
	v_mfma_f32_16x16x128_f8f6f4 v[72:75], v[18:25], v[206:213], v[72:75]
	v_mfma_f32_16x16x128_f8f6f4 v[68:71], v[26:33], v[206:213], v[68:71]
	v_mfma_f32_16x16x128_f8f6f4 v[56:59], v[18:25], v[214:221], v[56:59]
	v_mfma_f32_16x16x128_f8f6f4 v[52:55], v[26:33], v[214:221], v[52:55]
	v_mfma_f32_16x16x128_f8f6f4 v[40:43], v[18:25], v[240:247], v[40:43]
	v_mfma_f32_16x16x128_f8f6f4 v[36:39], v[26:33], v[240:247], v[36:39]
	s_barrier
	s_setprio 0
	s_add_i32 s42, s42, 2
	s_add_u32 s11, s11, 0x100
	s_addc_u32 s13, s13, 0
	s_cmp_gt_u32 s42, 41
	s_mov_b64 s[26:27], s[24:25]
	s_cbranch_scc0 .LBB0_462
.LBB0_462:
	s_add_u32 s24, s26, 0x100
	s_addc_u32 s25, s27, 0
	s_add_i32 s43, 0, 0x10000
	s_cmp_eq_u32 s42, 40
	s_cselect_b32 s31, s21, s25
	s_cselect_b32 s30, s20, s24
	s_cselect_b32 s29, s23, s13
	s_cselect_b32 s28, s22, s11
	s_add_i32 s60, 0, 0x14000
	v_add_u32_e32 v2, s43, v187
	v_add_u32_e32 v14, s60, v187
	ds_read_b128 v[18:21], v2
	ds_read_b128 v[22:25], v2 offset:1024
	ds_read_b128 v[26:29], v2 offset:2048
	ds_read_b128 v[30:33], v2 offset:3072
	ds_read_b128 v[2:5], v14
	ds_read_b128 v[6:9], v14 offset:1024
	ds_read_b128 v[10:13], v14 offset:2048
	ds_read_b128 v[14:17], v14 offset:3072
	v_lshl_add_u64 v[182:183], s[26:27], 0, v[170:171]
	s_add_i32 m0, s39, 0xc000
	ds_read_b128 v[174:177], v188
	ds_read_b128 v[178:181], v188 offset:1024
	ds_read_b128 v[190:193], v188 offset:2048
	ds_read_b128 v[194:197], v188 offset:3072
	ds_read_b128 v[206:209], v188 offset:4096
	ds_read_b128 v[210:213], v188 offset:5120
	ds_read_b128 v[214:217], v188 offset:6144
	ds_read_b128 v[218:221], v188 offset:7168
	global_load_lds_dwordx4 v[182:183], off
	v_lshl_add_u64 v[182:183], s[26:27], 0, v[172:173]
	s_add_i32 m0, s39, 0xe000
	s_nop 0
	global_load_lds_dwordx4 v[182:183], off
	s_waitcnt vmcnt(8)
	s_waitcnt lgkmcnt(0)
	s_setprio 1
	s_barrier
	v_mfma_f32_16x16x128_f8f6f4 v[160:163], v[18:25], v[174:181], v[160:163]
	v_mfma_f32_16x16x128_f8f6f4 v[156:159], v[26:33], v[174:181], v[156:159]
	v_mfma_f32_16x16x128_f8f6f4 v[144:147], v[18:25], v[190:197], v[144:147]
	v_mfma_f32_16x16x128_f8f6f4 v[140:143], v[26:33], v[190:197], v[140:143]
	v_mfma_f32_16x16x128_f8f6f4 v[128:131], v[18:25], v[206:213], v[128:131]
	v_mfma_f32_16x16x128_f8f6f4 v[124:127], v[26:33], v[206:213], v[124:127]
	v_mfma_f32_16x16x128_f8f6f4 v[112:115], v[18:25], v[214:221], v[112:115]
	v_mfma_f32_16x16x128_f8f6f4 v[108:111], v[26:33], v[214:221], v[108:111]
	v_mfma_f32_16x16x128_f8f6f4 v[152:155], v[2:9], v[174:181], v[152:155]
	v_mfma_f32_16x16x128_f8f6f4 v[148:151], v[10:17], v[174:181], v[148:151]
	v_mfma_f32_16x16x128_f8f6f4 v[136:139], v[2:9], v[190:197], v[136:139]
	v_mfma_f32_16x16x128_f8f6f4 v[132:135], v[10:17], v[190:197], v[132:135]
	v_mfma_f32_16x16x128_f8f6f4 v[120:123], v[2:9], v[206:213], v[120:123]
	v_mfma_f32_16x16x128_f8f6f4 v[116:119], v[10:17], v[206:213], v[116:119]
	v_mfma_f32_16x16x128_f8f6f4 v[104:107], v[2:9], v[214:221], v[104:107]
	v_mfma_f32_16x16x128_f8f6f4 v[100:103], v[10:17], v[214:221], v[100:103]
	s_barrier
	s_setprio 0
	s_add_i32 s26, s43, s38
	v_lshl_add_u64 v[174:175], s[28:29], 0, v[34:35]
	s_mov_b32 m0, s26
	ds_read_b128 v[190:193], v188 offset:16384
	ds_read_b128 v[194:197], v188 offset:17408
	ds_read_b128 v[206:209], v188 offset:18432
	ds_read_b128 v[210:213], v188 offset:19456
	ds_read_b128 v[214:217], v188 offset:20480
	ds_read_b128 v[218:221], v188 offset:21504
	ds_read_b128 v[240:243], v188 offset:22528
	ds_read_b128 v[244:247], v188 offset:23552
	global_load_lds_dwordx4 v[174:175], off
	s_add_i32 m0, s26, 0x2000
	s_add_u32 s26, s28, 0xb0000
	v_lshl_add_u64 v[176:177], s[28:29], 0, v[168:169]
	s_addc_u32 s27, s29, 0
	s_add_i32 s43, s60, s38
	global_load_lds_dwordx4 v[176:177], off
	v_lshl_add_u64 v[178:179], s[26:27], 0, v[34:35]
	s_mov_b32 m0, s43
	v_lshl_add_u64 v[180:181], s[30:31], 0, v[166:167]
	global_load_lds_dwordx4 v[178:179], off
	v_lshl_add_u64 v[178:179], s[26:27], 0, v[168:169]
	s_add_i32 m0, s43, 0x2000
	s_nop 0
	global_load_lds_dwordx4 v[178:179], off
	v_lshl_add_u64 v[178:179], s[30:31], 0, v[164:165]
	s_mov_b32 m0, s39
	s_nop 0
	global_load_lds_dwordx4 v[178:179], off
	s_mov_b32 m0, s44
	s_nop 0
	global_load_lds_dwordx4 v[180:181], off
	s_waitcnt vmcnt(8)
	s_waitcnt lgkmcnt(0)
	s_setprio 1
	s_barrier
	v_mfma_f32_16x16x128_f8f6f4 v[96:99], v[18:25], v[190:197], v[96:99]
	v_mfma_f32_16x16x128_f8f6f4 v[92:95], v[26:33], v[190:197], v[92:95]
	v_mfma_f32_16x16x128_f8f6f4 v[80:83], v[18:25], v[206:213], v[80:83]
	v_mfma_f32_16x16x128_f8f6f4 v[76:79], v[26:33], v[206:213], v[76:79]
	v_mfma_f32_16x16x128_f8f6f4 v[64:67], v[18:25], v[214:221], v[64:67]
	v_mfma_f32_16x16x128_f8f6f4 v[60:63], v[26:33], v[214:221], v[60:63]
	v_mfma_f32_16x16x128_f8f6f4 v[48:51], v[18:25], v[240:247], v[48:51]
	v_mfma_f32_16x16x128_f8f6f4 v[44:47], v[26:33], v[240:247], v[44:47]
	v_mfma_f32_16x16x128_f8f6f4 v[88:91], v[2:9], v[190:197], v[88:91]
	v_mfma_f32_16x16x128_f8f6f4 v[84:87], v[10:17], v[190:197], v[84:87]
	v_mfma_f32_16x16x128_f8f6f4 v[72:75], v[2:9], v[206:213], v[72:75]
	v_mfma_f32_16x16x128_f8f6f4 v[68:71], v[10:17], v[206:213], v[68:71]
	v_mfma_f32_16x16x128_f8f6f4 v[56:59], v[2:9], v[214:221], v[56:59]
	v_mfma_f32_16x16x128_f8f6f4 v[52:55], v[10:17], v[214:221], v[52:55]
	v_mfma_f32_16x16x128_f8f6f4 v[40:43], v[2:9], v[240:247], v[40:43]
	v_mfma_f32_16x16x128_f8f6f4 v[36:39], v[10:17], v[240:247], v[36:39]
	s_barrier
	s_setprio 0
	s_add_i32 s43, 0, 0x18000
	s_add_i32 s60, 0, 0x1c000
	v_add_u32_e32 v14, s43, v187
	v_add_u32_e32 v30, s60, v187
	ds_read_b128 v[2:5], v14
	ds_read_b128 v[6:9], v14 offset:1024
	ds_read_b128 v[10:13], v14 offset:2048
	ds_read_b128 v[14:17], v14 offset:3072
	ds_read_b128 v[18:21], v30
	ds_read_b128 v[22:25], v30 offset:1024
	ds_read_b128 v[26:29], v30 offset:2048
	ds_read_b128 v[30:33], v30 offset:3072
	s_add_u32 s26, s30, 0xb0000
	s_addc_u32 s27, s31, 0
	s_mov_b32 m0, s45
	v_lshl_add_u64 v[182:183], s[26:27], 0, v[164:165]
	ds_read_b128 v[190:193], v188 offset:32768
	ds_read_b128 v[194:197], v188 offset:33792
	ds_read_b128 v[206:209], v188 offset:34816
	ds_read_b128 v[210:213], v188 offset:35840
	ds_read_b128 v[214:217], v188 offset:36864
	ds_read_b128 v[218:221], v188 offset:37888
	ds_read_b128 v[240:243], v188 offset:38912
	ds_read_b128 v[244:247], v188 offset:39936
	global_load_lds_dwordx4 v[182:183], off
	v_lshl_add_u64 v[182:183], s[26:27], 0, v[166:167]
	s_mov_b32 m0, s46
	s_nop 0
	global_load_lds_dwordx4 v[182:183], off
	s_waitcnt vmcnt(8)
	s_waitcnt lgkmcnt(0)
	s_setprio 1
	s_barrier
	v_mfma_f32_16x16x128_f8f6f4 v[160:163], v[2:9], v[190:197], v[160:163]
	v_mfma_f32_16x16x128_f8f6f4 v[156:159], v[10:17], v[190:197], v[156:159]
	v_mfma_f32_16x16x128_f8f6f4 v[144:147], v[2:9], v[206:213], v[144:147]
	v_mfma_f32_16x16x128_f8f6f4 v[140:143], v[10:17], v[206:213], v[140:143]
	v_mfma_f32_16x16x128_f8f6f4 v[128:131], v[2:9], v[214:221], v[128:131]
	v_mfma_f32_16x16x128_f8f6f4 v[124:127], v[10:17], v[214:221], v[124:127]
	v_mfma_f32_16x16x128_f8f6f4 v[112:115], v[2:9], v[240:247], v[112:115]
	v_mfma_f32_16x16x128_f8f6f4 v[108:111], v[10:17], v[240:247], v[108:111]
	v_mfma_f32_16x16x128_f8f6f4 v[152:155], v[18:25], v[190:197], v[152:155]
	v_mfma_f32_16x16x128_f8f6f4 v[148:151], v[26:33], v[190:197], v[148:151]
	v_mfma_f32_16x16x128_f8f6f4 v[136:139], v[18:25], v[206:213], v[136:139]
	v_mfma_f32_16x16x128_f8f6f4 v[132:135], v[26:33], v[206:213], v[132:135]
	v_mfma_f32_16x16x128_f8f6f4 v[120:123], v[18:25], v[214:221], v[120:123]
	v_mfma_f32_16x16x128_f8f6f4 v[116:119], v[26:33], v[214:221], v[116:119]
	v_mfma_f32_16x16x128_f8f6f4 v[104:107], v[18:25], v[240:247], v[104:107]
	v_mfma_f32_16x16x128_f8f6f4 v[100:103], v[26:33], v[240:247], v[100:103]
	s_barrier
	s_setprio 0
	s_add_i32 s26, s43, s38
	v_lshl_add_u64 v[174:175], v[174:175], 0, s[18:19]
	s_mov_b32 m0, s26
	ds_read_b128 v[190:193], v188 offset:49152
	ds_read_b128 v[194:197], v188 offset:50176
	ds_read_b128 v[206:209], v188 offset:51200
	ds_read_b128 v[210:213], v188 offset:52224
	ds_read_b128 v[214:217], v188 offset:53248
	ds_read_b128 v[218:221], v188 offset:54272
	ds_read_b128 v[240:243], v188 offset:55296
	ds_read_b128 v[244:247], v188 offset:56320
	global_load_lds_dwordx4 v[174:175], off
	s_add_i32 m0, s26, 0x2000
	s_add_u32 s26, s28, 0xb0080
	v_lshl_add_u64 v[174:175], v[176:177], 0, s[18:19]
	s_addc_u32 s27, s29, 0
	s_add_i32 s28, s60, s38
	global_load_lds_dwordx4 v[174:175], off
	v_lshl_add_u64 v[174:175], s[26:27], 0, v[34:35]
	s_mov_b32 m0, s28
	s_nop 0
	global_load_lds_dwordx4 v[174:175], off
	v_lshl_add_u64 v[174:175], s[26:27], 0, v[168:169]
	s_add_i32 m0, s28, 0x2000
	s_nop 0
	global_load_lds_dwordx4 v[174:175], off
	v_lshl_add_u64 v[174:175], v[178:179], 0, s[18:19]
	s_mov_b32 m0, s47
	s_nop 0
	global_load_lds_dwordx4 v[174:175], off
	v_lshl_add_u64 v[174:175], v[180:181], 0, s[18:19]
	s_mov_b32 m0, s52
	s_nop 0
	global_load_lds_dwordx4 v[174:175], off
	s_waitcnt vmcnt(8)
	s_waitcnt lgkmcnt(0)
	s_setprio 1
	s_barrier
	v_mfma_f32_16x16x128_f8f6f4 v[96:99], v[2:9], v[190:197], v[96:99]
	v_mfma_f32_16x16x128_f8f6f4 v[92:95], v[10:17], v[190:197], v[92:95]
	v_mfma_f32_16x16x128_f8f6f4 v[80:83], v[2:9], v[206:213], v[80:83]
	v_mfma_f32_16x16x128_f8f6f4 v[76:79], v[10:17], v[206:213], v[76:79]
	v_mfma_f32_16x16x128_f8f6f4 v[64:67], v[2:9], v[214:221], v[64:67]
	v_mfma_f32_16x16x128_f8f6f4 v[60:63], v[10:17], v[214:221], v[60:63]
	v_mfma_f32_16x16x128_f8f6f4 v[48:51], v[2:9], v[240:247], v[48:51]
	v_mfma_f32_16x16x128_f8f6f4 v[44:47], v[10:17], v[240:247], v[44:47]
	v_mfma_f32_16x16x128_f8f6f4 v[88:91], v[18:25], v[190:197], v[88:91]
	v_mfma_f32_16x16x128_f8f6f4 v[84:87], v[26:33], v[190:197], v[84:87]
	v_mfma_f32_16x16x128_f8f6f4 v[72:75], v[18:25], v[206:213], v[72:75]
	v_mfma_f32_16x16x128_f8f6f4 v[68:71], v[26:33], v[206:213], v[68:71]
	v_mfma_f32_16x16x128_f8f6f4 v[56:59], v[18:25], v[214:221], v[56:59]
	v_mfma_f32_16x16x128_f8f6f4 v[52:55], v[26:33], v[214:221], v[52:55]
	v_mfma_f32_16x16x128_f8f6f4 v[40:43], v[18:25], v[240:247], v[40:43]
	v_mfma_f32_16x16x128_f8f6f4 v[36:39], v[26:33], v[240:247], v[36:39]
	s_barrier
	s_setprio 0
	s_add_i32 s42, s42, 2
	s_add_u32 s11, s11, 0x100
	s_addc_u32 s13, s13, 0
	s_cmp_gt_u32 s42, 41
	s_mov_b64 s[26:27], s[24:25]
	s_cbranch_scc0 .LBB0_462
	s_and_b64 vcc, exec, s[16:17]
	s_cbranch_vccz .LBB0_465
	s_barrier

.LBB0_502:
	s_add_i32 s52, 0, 0x10000
	s_cmp_eq_u32 s43, 40
	s_cselect_b32 s27, s21, s13
	s_cselect_b32 s26, s20, s11
	s_cselect_b32 s25, s23, s42
	s_cselect_b32 s24, s22, s29
	s_add_i32 s55, 0, 0x14000
	v_add_u32_e32 v80, s52, v111
	v_add_u32_e32 v96, s55, v111
	ds_read_b128 v[68:71], v80
	ds_read_b128 v[72:75], v80 offset:1024
	ds_read_b128 v[76:79], v80 offset:2048
	ds_read_b128 v[80:83], v80 offset:3072
	ds_read_b128 v[84:87], v96
	ds_read_b128 v[88:91], v96 offset:1024
	ds_read_b128 v[92:95], v96 offset:2048
	ds_read_b128 v[96:99], v96 offset:3072
	ds_read_b128 v[100:103], v112
	ds_read_b128 v[104:107], v112 offset:1024
	ds_read_b128 v[114:117], v112 offset:2048
	ds_read_b128 v[118:121], v112 offset:3072
	ds_read_b128 v[122:125], v112 offset:4096
	ds_read_b128 v[126:129], v112 offset:5120
	ds_read_b128 v[130:133], v112 offset:6144
	ds_read_b128 v[134:137], v112 offset:7168
	s_waitcnt lgkmcnt(0)
	s_barrier
	s_setprio 1
	s_waitcnt lgkmcnt(0)
	v_mfma_f32_16x16x128_f8f6f4 v[64:67], v[68:75], v[100:107], v[64:67]
	v_mfma_f32_16x16x128_f8f6f4 v[60:63], v[76:83], v[100:107], v[60:63]
	v_mfma_f32_16x16x128_f8f6f4 v[48:51], v[68:75], v[114:121], v[48:51]
	v_mfma_f32_16x16x128_f8f6f4 v[44:47], v[76:83], v[114:121], v[44:47]
	v_mfma_f32_16x16x128_f8f6f4 v[30:33], v[68:75], v[122:129], v[30:33]
	v_mfma_f32_16x16x128_f8f6f4 v[26:29], v[76:83], v[122:129], v[26:29]
	v_mfma_f32_16x16x128_f8f6f4 v[14:17], v[68:75], v[130:137], v[14:17]
	v_mfma_f32_16x16x128_f8f6f4 v[10:13], v[76:83], v[130:137], v[10:13]
	s_setprio 0
	s_setprio 1
	v_mfma_f32_16x16x128_f8f6f4 v[56:59], v[84:91], v[100:107], v[56:59]
	v_mfma_f32_16x16x128_f8f6f4 v[52:55], v[92:99], v[100:107], v[52:55]
	v_mfma_f32_16x16x128_f8f6f4 v[40:43], v[84:91], v[114:121], v[40:43]
	v_mfma_f32_16x16x128_f8f6f4 v[36:39], v[92:99], v[114:121], v[36:39]
	v_mfma_f32_16x16x128_f8f6f4 v[22:25], v[84:91], v[122:129], v[22:25]
	v_mfma_f32_16x16x128_f8f6f4 v[18:21], v[92:99], v[122:129], v[18:21]
	v_mfma_f32_16x16x128_f8f6f4 v[6:9], v[84:91], v[130:137], v[6:9]
	v_mfma_f32_16x16x128_f8f6f4 v[2:5], v[92:99], v[130:137], v[2:5]
	s_setprio 0
	s_barrier
	s_add_i32 s52, s52, s30
	v_lshl_add_u64 v[108:109], s[24:25], 0, v[34:35]
	s_mov_b32 m0, s52
	v_lshl_add_u64 v[138:139], s[24:25], 0, v[168:169]
	global_load_lds_dwordx4 v[108:109], off
	s_add_i32 m0, s52, 0x2000
	s_add_u32 s60, s24, 0xb0000
	s_addc_u32 s61, s25, 0
	s_add_i32 s52, s55, s30
	global_load_lds_dwordx4 v[138:139], off
	v_lshl_add_u64 v[68:69], s[60:61], 0, v[34:35]
	s_mov_b32 m0, s52
	v_lshl_add_u64 v[140:141], s[26:27], 0, v[164:165]
	global_load_lds_dwordx4 v[68:69], off
	v_lshl_add_u64 v[68:69], s[60:61], 0, v[168:169]
	s_add_i32 m0, s52, 0x2000
	v_lshl_add_u64 v[142:143], s[26:27], 0, v[166:167]
	global_load_lds_dwordx4 v[68:69], off
	s_mov_b32 m0, s31
	s_nop 0
	global_load_lds_dwordx4 v[140:141], off
	s_mov_b32 m0, s38
	s_nop 0
	global_load_lds_dwordx4 v[142:143], off
	s_waitcnt vmcnt(6)
	s_barrier
	s_barrier
	s_add_i32 s26, 0, 0x18000
	s_add_i32 s27, 0, 0x1c000
	v_add_u32_e32 v80, s26, v111
	v_add_u32_e32 v96, s27, v111
	ds_read_b128 v[68:71], v80
	ds_read_b128 v[72:75], v80 offset:1024
	ds_read_b128 v[76:79], v80 offset:2048
	ds_read_b128 v[80:83], v80 offset:3072
	ds_read_b128 v[84:87], v96
	ds_read_b128 v[88:91], v96 offset:1024
	ds_read_b128 v[92:95], v96 offset:2048
	ds_read_b128 v[96:99], v96 offset:3072
	ds_read_b128 v[100:103], v112 offset:32768
	ds_read_b128 v[104:107], v112 offset:33792
	ds_read_b128 v[114:117], v112 offset:34816
	ds_read_b128 v[118:121], v112 offset:35840
	ds_read_b128 v[122:125], v112 offset:36864
	ds_read_b128 v[126:129], v112 offset:37888
	ds_read_b128 v[130:133], v112 offset:38912
	ds_read_b128 v[134:137], v112 offset:39936
	s_waitcnt lgkmcnt(0)
	s_barrier
	s_setprio 1
	s_waitcnt lgkmcnt(0)
	v_mfma_f32_16x16x128_f8f6f4 v[64:67], v[68:75], v[100:107], v[64:67]
	v_mfma_f32_16x16x128_f8f6f4 v[60:63], v[76:83], v[100:107], v[60:63]
	v_mfma_f32_16x16x128_f8f6f4 v[48:51], v[68:75], v[114:121], v[48:51]
	v_mfma_f32_16x16x128_f8f6f4 v[44:47], v[76:83], v[114:121], v[44:47]
	v_mfma_f32_16x16x128_f8f6f4 v[30:33], v[68:75], v[122:129], v[30:33]
	v_mfma_f32_16x16x128_f8f6f4 v[26:29], v[76:83], v[122:129], v[26:29]
	v_mfma_f32_16x16x128_f8f6f4 v[14:17], v[68:75], v[130:137], v[14:17]
	v_mfma_f32_16x16x128_f8f6f4 v[10:13], v[76:83], v[130:137], v[10:13]
	s_setprio 0
	s_setprio 1
	v_mfma_f32_16x16x128_f8f6f4 v[56:59], v[84:91], v[100:107], v[56:59]
	v_mfma_f32_16x16x128_f8f6f4 v[52:55], v[92:99], v[100:107], v[52:55]
	v_mfma_f32_16x16x128_f8f6f4 v[40:43], v[84:91], v[114:121], v[40:43]
	v_mfma_f32_16x16x128_f8f6f4 v[36:39], v[92:99], v[114:121], v[36:39]
	v_mfma_f32_16x16x128_f8f6f4 v[22:25], v[84:91], v[122:129], v[22:25]
	v_mfma_f32_16x16x128_f8f6f4 v[18:21], v[92:99], v[122:129], v[18:21]
	v_mfma_f32_16x16x128_f8f6f4 v[6:9], v[84:91], v[130:137], v[6:9]
	v_mfma_f32_16x16x128_f8f6f4 v[2:5], v[92:99], v[130:137], v[2:5]
	s_setprio 0
	s_barrier
	s_add_i32 s26, s26, s30
	v_lshl_add_u64 v[68:69], v[108:109], 0, s[18:19]
	s_mov_b32 m0, s26
	s_nop 0
	global_load_lds_dwordx4 v[68:69], off
	s_add_i32 m0, s26, 0x2000
	s_add_u32 s24, s24, 0xb0080
	v_lshl_add_u64 v[68:69], v[138:139], 0, s[18:19]
	s_addc_u32 s25, s25, 0
	s_add_i32 s26, s27, s30
	global_load_lds_dwordx4 v[68:69], off
	v_lshl_add_u64 v[68:69], s[24:25], 0, v[34:35]
	s_mov_b32 m0, s26
	s_nop 0
	global_load_lds_dwordx4 v[68:69], off
	v_lshl_add_u64 v[68:69], s[24:25], 0, v[168:169]
	s_add_i32 m0, s26, 0x2000
	s_nop 0
	global_load_lds_dwordx4 v[68:69], off
	v_lshl_add_u64 v[68:69], v[140:141], 0, s[18:19]
	s_mov_b32 m0, s39
	s_nop 0
	global_load_lds_dwordx4 v[68:69], off
	v_lshl_add_u64 v[68:69], v[142:143], 0, s[18:19]
	s_mov_b32 m0, s44
	s_nop 0
	global_load_lds_dwordx4 v[68:69], off
	s_waitcnt vmcnt(6)
	s_barrier
	s_barrier
	s_add_i32 s43, s43, 2
	s_add_u32 s11, s11, 0x100
	s_addc_u32 s13, s13, 0
	s_add_u32 s29, s29, 0x100
	s_addc_u32 s42, s42, 0
	s_cmp_gt_u32 s43, 41
	s_cbranch_scc0 .LBB0_502
	s_and_b64 vcc, exec, s[16:17]
	s_cbranch_vccz .LBB0_505
	s_barrier
